# ping-pong attention loop: K-tile global loads issued one segment earlier (loop top / start of the vector segment) and every vmcnt wait counted against the new issue order, so the K-tile LDS write no l
# speedup vs baseline: 1.0123x; 1.0026x over previous
; __device__ __forceinline__ void finishSM(f32x16& p0, f32x16& p1, float alpha, float& l_reg, bf16x8& pa0, bf16x8& pa1, bf16x8& pa2, bf16x8& pa3) {
;     ...
;     for (int r = 0; r < 16; ++r) p1[r] = __builtin_amdgcn_exp2f(p1[r]);
;     float ps = 0;
; #pragma unroll
;     for (int r = 0; r < 16; ++r) ps += p0[r];
; #pragma unroll
;     for (int r = 0; r < 16; ++r) ps += p1[r];
;     { auto rr = __builtin_amdgcn_permlane32_swap(__float_as_uint(ps), __float_as_uint(ps), false, false);
;       ps = __uint_as_float(rr[0]) + __uint_as_float(rr[1]); }
;     l_reg = l_reg * alpha + ps;
;     ...
;     PK4(p0, 0, pa0); PK4(p0, 8, pa1); PK4(p1, 0, pa2); PK4(p1, 8, pa3);
.Lp5_lead:
.LBB0_1299:
	s_add_u32 s98, s100, 0x40000
	s_addc_u32 s99, s101, 0
	global_load_dwordx4 v[138:141], v188, s[98:99]
	s_add_u32 s98, s100, 0x50000
	s_addc_u32 s99, s101, 0
	global_load_dwordx4 v[142:145], v188, s[98:99]
	v_exp_f32_e32 v209, v150
	v_add_f32_e32 v150, v220, v219
	v_add_f32_e32 v150, v221, v150
	v_add_f32_e32 v150, v222, v150
	v_add_f32_e32 v150, v223, v150
	v_add_f32_e32 v150, v225, v150
	v_add_f32_e32 v150, v224, v150
	v_add_f32_e32 v150, v226, v150
	v_add_f32_e32 v150, v211, v150
	v_add_f32_e32 v150, v212, v150
	v_exp_f32_e32 v194, v194
	v_exp_f32_e32 v195, v195
	v_exp_f32_e32 v192, v192
	v_exp_f32_e32 v193, v193
	v_exp_f32_e32 v158, v158
	v_exp_f32_e32 v159, v159
	v_exp_f32_e32 v207, v154
	v_exp_f32_e32 v208, v155
	v_exp_f32_e32 v210, v151
	v_exp_f32_e32 v160, v160
	v_exp_f32_e32 v161, v161
	v_exp_f32_e32 v227, v156
	v_cvt_pk_bf16_f32 v151, v224, v226
	v_cvt_pk_bf16_f32 v154, v214, v216
	v_cvt_pk_bf16_f32 v155, v217, v218
	v_cvt_pk_bf16_f32 v156, v194, v195
	v_exp_f32_e32 v228, v157
	v_exp_f32_e32 v229, v152
	v_exp_f32_e32 v230, v153
	v_cvt_pk_bf16_f32 v152, v211, v212
	v_cvt_pk_bf16_f32 v153, v213, v215
	v_cvt_pk_bf16_f32 v157, v192, v193
	v_cvt_pk_bf16_f32 v211, v229, v230
	v_add_f32_e32 v249, v213, v150
	v_add_f32_e32 v249, v215, v249
	v_add_f32_e32 v249, v214, v249
	v_add_f32_e32 v249, v216, v249
	v_add_f32_e32 v249, v217, v249
	v_add_f32_e32 v249, v218, v249
	v_add_f32_e32 v249, v194, v249
	v_add_f32_e32 v248, v195, v249
	v_add_f32_e32 v248, v192, v248
	v_add_f32_e32 v248, v193, v248
	v_add_f32_e32 v248, v158, v248
	v_add_f32_e32 v248, v159, v248
	v_add_f32_e32 v248, v207, v248
	v_add_f32_e32 v248, v208, v248
	v_add_f32_e32 v248, v209, v248
	v_add_f32_e32 v248, v210, v248
	v_add_f32_e32 v248, v160, v248
	v_add_f32_e32 v248, v161, v248
	v_add_f32_e32 v248, v227, v248
	v_add_f32_e32 v248, v228, v248
	v_add_f32_e32 v248, v229, v248
	v_add_f32_e32 v181, v230, v248
	v_cvt_pk_bf16_f32 v148, v219, v220
	v_cvt_pk_bf16_f32 v149, v221, v222
	v_cvt_pk_bf16_f32 v150, v223, v225
	v_cvt_pk_bf16_f32 v158, v158, v159
	v_cvt_pk_bf16_f32 v159, v207, v208
	v_cvt_pk_bf16_f32 v208, v209, v210
	v_cvt_pk_bf16_f32 v210, v227, v228
	v_cvt_pk_bf16_f32 v209, v160, v161
	s_waitcnt lgkmcnt(0)
	s_barrier
	s_cmp_eq_u32 s76, 0
	s_cbranch_scc1 .Lp5_vw_a
	s_waitcnt vmcnt(2)
	ds_write_b128 v197, v[130:133] offset:16384
	ds_write_b128 v198, v[134:137] offset:16384
; template <int KB>
; __device__ __forceinline__ void qkt(f32x16& p0, f32x16& p1, const char* K_lds, int r32, int hi, const bf16x8* qr) {
;     ...
;     for (int d0 = 0; d0 < 8; ++d0) { const char* a = kb[d0 & 3] + (d0 >> 2) * 128;
;         bf16x8 b0 = *reinterpret_cast<const bf16x8*>(a);
;         bf16x8 b1 = *reinterpret_cast<const bf16x8*>(a + 32 * 256);
;         p0 = __builtin_amdgcn_mfma_f32_32x32x16_bf16(b0, qr[d0], p0, 0, 0, 0);
;         p1 = __builtin_amdgcn_mfma_f32_32x32x16_bf16(b1, qr[d0], p1, 0, 0, 0); }
; }
; template <int VB>
; __device__ __forceinline__ void pv_tile(f32x16* o, int vb0, bf16x8 pa0, bf16x8 pa1, bf16x8 pa2, bf16x8 pa3) {
;     ...
;     PV_D0(0); PV_D0(1); PV_D0(2); PV_D0(3);
;     ...
; }
.Lp5_vw_a:
	global_load_dwordx2 v[146:147], v179, s[68:69] offset:-8
	s_add_u32 s98, s16, 0x40000
	s_addc_u32 s99, s17, 0
	global_load_dwordx4 v[130:133], v188, s[98:99]
	s_add_u32 s98, s16, 0x50000
	s_addc_u32 s99, s17, 0
	global_load_dwordx4 v[134:137], v188, s[98:99]
	ds_read_b128 v[66:69], v199 offset:49152
	ds_read_b128 v[82:85], v199 offset:57344
	ds_read_b128 v[172:175], v200 offset:49152
	ds_read_b128 v[232:235], v200 offset:57344
	ds_read_b128 v[236:239], v201 offset:49152
	ds_read_b128 v[240:243], v201 offset:57344
	ds_read_b128 v[244:247], v202 offset:49152
	s_waitcnt lgkmcnt(6)
	v_mfma_f32_32x32x16_bf16 v[66:81], v[66:69], v[126:129], 0
	s_waitcnt lgkmcnt(5)
	v_mfma_f32_32x32x16_bf16 v[82:97], v[82:85], v[126:129], 0
	s_waitcnt lgkmcnt(4)
	v_mfma_f32_32x32x16_bf16 v[66:81], v[172:175], v[122:125], v[66:81]
	ds_read_b128 v[172:175], v202 offset:57344
	s_waitcnt lgkmcnt(4)
	v_mfma_f32_32x32x16_bf16 v[82:97], v[232:235], v[122:125], v[82:97]
	ds_read_b128 v[232:235], v199 offset:49280
	s_waitcnt lgkmcnt(4)
	v_mfma_f32_32x32x16_bf16 v[66:81], v[236:239], v[118:121], v[66:81]
	ds_read_b128 v[236:239], v199 offset:57472
	s_waitcnt lgkmcnt(4)
	v_mfma_f32_32x32x16_bf16 v[82:97], v[240:243], v[118:121], v[82:97]
	ds_read_b128 v[240:243], v200 offset:49280
	s_waitcnt lgkmcnt(4)
	v_mfma_f32_32x32x16_bf16 v[66:81], v[244:247], v[114:117], v[66:81]
	ds_read_b128 v[244:247], v200 offset:57472
	s_waitcnt lgkmcnt(4)
	v_mfma_f32_32x32x16_bf16 v[82:97], v[172:175], v[114:117], v[82:97]
	ds_read_b128 v[172:175], v201 offset:49280
	s_waitcnt lgkmcnt(4)
	v_mfma_f32_32x32x16_bf16 v[66:81], v[232:235], v[110:113], v[66:81]
	ds_read_b128 v[232:235], v201 offset:57472
	s_waitcnt lgkmcnt(4)
	v_mfma_f32_32x32x16_bf16 v[82:97], v[236:239], v[110:113], v[82:97]
	ds_read_b128 v[236:239], v202 offset:49280
	s_waitcnt lgkmcnt(4)
	v_mfma_f32_32x32x16_bf16 v[66:81], v[240:243], v[106:109], v[66:81]
	ds_read_b64_tr_b16 v[212:213], v1 offset:0x0
	ds_read_b64_tr_b16 v[214:215], v1 offset:0x800
	ds_read_b64_tr_b16 v[216:217], v1 offset:0x200
	ds_read_b64_tr_b16 v[218:219], v1 offset:0xa00
	ds_read_b64_tr_b16 v[220:221], v1 offset:0x400
	ds_read_b64_tr_b16 v[222:223], v1 offset:0xc00
	ds_read_b64_tr_b16 v[224:225], v1 offset:0x600
	ds_read_b64_tr_b16 v[226:227], v1 offset:0xe00
	ds_read_b128 v[240:243], v202 offset:57472
	s_waitcnt lgkmcnt(12)
	v_mfma_f32_32x32x16_bf16 v[82:97], v[244:247], v[106:109], v[82:97]
	s_waitcnt lgkmcnt(11)
	v_mfma_f32_32x32x16_bf16 v[66:81], v[172:175], v[102:105], v[66:81]
	s_waitcnt lgkmcnt(10)
	v_mfma_f32_32x32x16_bf16 v[82:97], v[232:235], v[102:105], v[82:97]
	s_waitcnt lgkmcnt(9)
	v_mfma_f32_32x32x16_bf16 v[66:81], v[236:239], v[98:101], v[66:81]
	s_waitcnt lgkmcnt(0)
	v_mfma_f32_32x32x16_bf16 v[82:97], v[240:243], v[98:101], v[82:97]
	ds_read_b64_tr_b16 v[248:249], v1 offset:0x1000
	ds_read_b64_tr_b16 v[250:251], v1 offset:0x1800
	ds_read_b64_tr_b16 v[172:173], v1 offset:0x1200
	ds_read_b64_tr_b16 v[174:175], v1 offset:0x1a00
	ds_read_b64_tr_b16 v[232:233], v1 offset:0x1400
	ds_read_b64_tr_b16 v[234:235], v1 offset:0x1c00
	s_waitcnt lgkmcnt(13)
	v_mfma_f32_32x32x16_bf16 v[2:17], v[148:151], v[212:215], v[2:17]
	ds_read_b64_tr_b16 v[236:237], v1 offset:0x1600
	ds_read_b64_tr_b16 v[238:239], v1 offset:0x1e00
	s_waitcnt lgkmcnt(13)
	v_mfma_f32_32x32x16_bf16 v[50:65], v[148:151], v[216:219], v[50:65]
	ds_read_b64_tr_b16 v[240:241], v1 offset:0x2000
	ds_read_b64_tr_b16 v[242:243], v1 offset:0x2800
	s_waitcnt lgkmcnt(13)
	v_mfma_f32_32x32x16_bf16 v[34:49], v[148:151], v[220:223], v[34:49]
	ds_read_b64_tr_b16 v[244:245], v1 offset:0x2200
	ds_read_b64_tr_b16 v[246:247], v1 offset:0x2a00
	s_waitcnt lgkmcnt(13)
	v_mfma_f32_32x32x16_bf16 v[18:33], v[148:151], v[224:227], v[18:33]
	ds_read_b64_tr_b16 v[224:225], v1 offset:0x2400
	ds_read_b64_tr_b16 v[226:227], v1 offset:0x2c00
	s_waitcnt lgkmcnt(12)
	v_mfma_f32_32x32x16_bf16 v[2:17], v[152:155], v[248:251], v[2:17]
	ds_read_b64_tr_b16 v[248:249], v1 offset:0x2600
	ds_read_b64_tr_b16 v[250:251], v1 offset:0x2e00
	s_waitcnt lgkmcnt(12)
	v_mfma_f32_32x32x16_bf16 v[50:65], v[152:155], v[172:175], v[50:65]
	ds_read_b64_tr_b16 v[172:173], v1 offset:0x3000
	ds_read_b64_tr_b16 v[174:175], v1 offset:0x3800
	s_waitcnt lgkmcnt(12)
	v_mfma_f32_32x32x16_bf16 v[34:49], v[152:155], v[232:235], v[34:49]
	ds_read_b64_tr_b16 v[232:233], v1 offset:0x3200
	ds_read_b64_tr_b16 v[234:235], v1 offset:0x3a00
	s_waitcnt lgkmcnt(12)
	v_mfma_f32_32x32x16_bf16 v[18:33], v[152:155], v[236:239], v[18:33]
	ds_read_b64_tr_b16 v[236:237], v1 offset:0x3400
	ds_read_b64_tr_b16 v[238:239], v1 offset:0x3c00
	s_waitcnt lgkmcnt(12)
	v_mfma_f32_32x32x16_bf16 v[2:17], v[156:159], v[240:243], v[2:17]
	ds_read_b64_tr_b16 v[240:241], v1 offset:0x3600
	ds_read_b64_tr_b16 v[242:243], v1 offset:0x3e00
	s_waitcnt lgkmcnt(12)
	v_mfma_f32_32x32x16_bf16 v[50:65], v[156:159], v[244:247], v[50:65]
	s_waitcnt lgkmcnt(10)
	v_mfma_f32_32x32x16_bf16 v[34:49], v[156:159], v[224:227], v[34:49]
	s_waitcnt lgkmcnt(8)
	v_mfma_f32_32x32x16_bf16 v[18:33], v[156:159], v[248:251], v[18:33]
	s_waitcnt lgkmcnt(6)
	v_mfma_f32_32x32x16_bf16 v[2:17], v[208:211], v[172:175], v[2:17]
	s_waitcnt lgkmcnt(4)
	v_mfma_f32_32x32x16_bf16 v[50:65], v[208:211], v[232:235], v[50:65]
	s_waitcnt lgkmcnt(2)
	v_mfma_f32_32x32x16_bf16 v[34:49], v[208:211], v[236:239], v[34:49]
	s_waitcnt lgkmcnt(0)
	v_mfma_f32_32x32x16_bf16 v[18:33], v[208:211], v[240:243], v[18:33]
	s_waitcnt vmcnt(3)
	ds_write_b128 v204, v[138:141] offset:32768
	ds_write_b128 v204, v[142:145] offset:40960
	s_waitcnt lgkmcnt(0)
	s_barrier
	s_add_i32 s98, s82, 2
	s_cmp_gt_u32 s98, s81
	s_cbranch_scc1 .Lp5_k2_skip
	s_add_u32 s98, s100, 0x60000
	s_addc_u32 s99, s101, 0
	global_load_dwordx4 v[138:141], v188, s[98:99]
	s_add_u32 s98, s100, 0x70000
	s_addc_u32 s99, s101, 0
	global_load_dwordx4 v[142:145], v188, s[98:99]
	s_branch .Lp5_k2_done

; __device__ __forceinline__ void sel_mask_tile(f32x16& p0, f32x16& p1, unsigned wlo, unsigned whi, int hi) {
;     const unsigned NEGB = 0xff800000u;
;     const unsigned lo = wlo >> (4 * hi), h2 = whi >> (4 * hi);
; #pragma unroll
;     for (int r = 0; r < 16; ++r) {
;         const int c = (r & 3) + 8 * (r >> 2);
;         const unsigned m0 = (unsigned)__builtin_amdgcn_sbfe((int)lo, c, 1), m1 = (unsigned)__builtin_amdgcn_sbfe((int)h2, c, 1);
;         p0[r] = __uint_as_float((__float_as_uint(p0[r]) & m0) | (NEGB & ~m0));
;         p1[r] = __uint_as_float((__float_as_uint(p1[r]) & m1) | (NEGB & ~m1));
;     }
; }
; __device__ __forceinline__ void partialSM(f32x16& p0, f32x16& p1, float& m_reg, float& mn, float& alpha) {
;     float pmax = p0[0];
; #pragma unroll
;     for (int r = 1; r < 16; ++r) pmax = fmaxf(pmax, p0[r]);
; #pragma unroll
;     for (int r = 0; r < 16; ++r) pmax = fmaxf(pmax, p1[r]);
;     { auto rr = __builtin_amdgcn_permlane32_swap(__float_as_uint(pmax), __float_as_uint(pmax), false, false);
;       pmax = fmaxf(__uint_as_float(rr[0]), __uint_as_float(rr[1])); }
;     constexpr float C2 = 1.4426950408889634f * SCALE;
;     if (__builtin_expect(__all((pmax - m_reg) * SCALE <= THR), 1)) { mn = m_reg; alpha = 1.f; }
;     else { mn = fmaxf(m_reg, pmax); alpha = __builtin_amdgcn_exp2f((m_reg - mn) * C2); m_reg = mn; }
.Lp5_k2_done:
	s_nop 0
	s_waitcnt vmcnt(4)
	v_lshrrev_b32_e32 v160, v163, v146
	v_lshrrev_b32_e32 v161, v163, v147
	v_bfe_i32 v146, v160, 0, 1
	v_bfe_i32 v147, v161, 0, 1
	v_bitop3_b32 v146, v66, s74, v146 bitop3:0xe4
	v_bitop3_b32 v66, v82, s74, v147 bitop3:0xe4
	v_bfe_i32 v82, v160, 1, 1
	v_bfe_i32 v147, v161, 1, 1
	v_bitop3_b32 v82, v67, s74, v82 bitop3:0xe4
	v_bitop3_b32 v67, v83, s74, v147 bitop3:0xe4
	v_bfe_i32 v83, v160, 2, 1
	v_bfe_i32 v147, v161, 2, 1
	v_bitop3_b32 v83, v68, s74, v83 bitop3:0xe4
	v_bitop3_b32 v68, v84, s74, v147 bitop3:0xe4
	v_bfe_i32 v84, v160, 3, 1
	v_bfe_i32 v148, v161, 3, 1
	v_bitop3_b32 v147, v69, s74, v84 bitop3:0xe4
	v_bfe_i32 v84, v160, 8, 1
	v_bitop3_b32 v69, v85, s74, v148 bitop3:0xe4
	v_bfe_i32 v85, v161, 8, 1
	v_bitop3_b32 v148, v70, s74, v84 bitop3:0xe4
	v_bfe_i32 v84, v160, 9, 1
	v_bitop3_b32 v70, v86, s74, v85 bitop3:0xe4
	v_bfe_i32 v85, v161, 9, 1
	v_bitop3_b32 v149, v71, s74, v84 bitop3:0xe4
	v_bfe_i32 v84, v160, 10, 1
	v_bitop3_b32 v71, v87, s74, v85 bitop3:0xe4
	v_bfe_i32 v85, v161, 10, 1
	v_bitop3_b32 v87, v72, s74, v84 bitop3:0xe4
	v_bfe_i32 v84, v160, 11, 1
	v_bitop3_b32 v72, v88, s74, v85 bitop3:0xe4
	v_bfe_i32 v85, v161, 11, 1
	v_bitop3_b32 v88, v73, s74, v84 bitop3:0xe4
	v_bfe_i32 v73, v160, 16, 1
	v_bitop3_b32 v84, v89, s74, v85 bitop3:0xe4
	v_bfe_i32 v85, v161, 16, 1
	v_bitop3_b32 v89, v74, s74, v73 bitop3:0xe4
	v_bfe_i32 v73, v160, 17, 1
	v_bfe_i32 v74, v161, 17, 1
	v_bitop3_b32 v85, v90, s74, v85 bitop3:0xe4
	v_bitop3_b32 v90, v75, s74, v73 bitop3:0xe4
	v_bitop3_b32 v86, v91, s74, v74 bitop3:0xe4
	v_bfe_i32 v73, v160, 18, 1
	v_bfe_i32 v74, v161, 18, 1
	v_bitop3_b32 v91, v76, s74, v73 bitop3:0xe4
	v_bitop3_b32 v76, v92, s74, v74 bitop3:0xe4
	v_bfe_i32 v73, v160, 19, 1
	v_bfe_i32 v74, v161, 19, 1
	v_bitop3_b32 v92, v77, s74, v73 bitop3:0xe4
	v_bitop3_b32 v77, v93, s74, v74 bitop3:0xe4
	v_bfe_i32 v73, v160, 24, 1
	v_bfe_i32 v74, v161, 24, 1
	v_bitop3_b32 v93, v78, s74, v73 bitop3:0xe4
	v_bitop3_b32 v78, v94, s74, v74 bitop3:0xe4
	v_bfe_i32 v73, v160, 25, 1
	v_bfe_i32 v74, v161, 25, 1
	v_bitop3_b32 v79, v79, s74, v73 bitop3:0xe4
	v_bitop3_b32 v73, v95, s74, v74 bitop3:0xe4
	v_bfe_i32 v74, v160, 26, 1
	v_bfe_i32 v75, v161, 26, 1
	v_bitop3_b32 v80, v80, s74, v74 bitop3:0xe4
	v_bitop3_b32 v74, v96, s74, v75 bitop3:0xe4
	v_bfe_i32 v75, v160, 27, 1
	v_bfe_i32 v94, v161, 27, 1
	v_bitop3_b32 v81, v81, s74, v75 bitop3:0xe4
	v_bitop3_b32 v75, v97, s74, v94 bitop3:0xe4
	v_max_f32_e32 v94, v146, v82
	v_max3_f32 v94, v94, v83, v147
	v_max3_f32 v94, v94, v148, v149
	v_max3_f32 v94, v94, v87, v88
	v_max3_f32 v94, v94, v89, v90
	v_max3_f32 v94, v94, v91, v92
	v_max3_f32 v94, v94, v93, v79
	v_max3_f32 v94, v94, v80, v81
	v_max3_f32 v94, v94, v66, v67
	v_max3_f32 v94, v94, v68, v69
	v_max3_f32 v94, v94, v70, v71
	v_max3_f32 v94, v94, v72, v84
	v_max3_f32 v94, v94, v85, v86
	v_max3_f32 v94, v94, v76, v77
	v_max3_f32 v94, v94, v78, v73
	v_max3_f32 v94, v94, v74, v75
	v_mov_b32_e32 v95, v94
	s_nop 1
	v_permlane32_swap_b32_e32 v94, v95
	v_max_f32_e32 v94, v94, v95
	v_sub_f32_e32 v95, v94, v206
	v_mul_f32_e32 v95, 0x3db504f3, v95
	v_cmp_ge_f32_e32 vcc, s75, v95
	s_cmp_eq_u64 vcc, exec
	s_cselect_b64 s[6:7], -1, 0
	s_cbranch_scc1 .Lp5_b1fast
	v_max_f32_e32 v94, v206, v94
	v_sub_f32_e32 v96, v206, v94
	v_mul_f32_e32 v96, 0x3e0293ee, v96
	v_exp_f32_e32 v96, v96
.Lp5_b1fast:
	s_nop 0
	v_cndmask_b32_e64 v208, v96, 1.0, s[6:7]
	s_not_b64 vcc, s[6:7]
	s_cbranch_vccz .LBB0_1303
	v_mov_b32_e32 v206, v94
	v_mul_f32_e32 v190, 0xbe0293ee, v94
	s_and_saveexec_b64 s[36:37], s[0:1]
	ds_write_b32 v185, v208 offset:128
	s_or_b64 exec, exec, s[36:37]
	s_waitcnt lgkmcnt(0)
	ds_read_b128 v[150:153], v183 offset:224
	ds_read_b128 v[154:157], v183 offset:192
	ds_read_b128 v[158:161], v183 offset:160
	ds_read_b128 v[172:175], v183 offset:128
	s_waitcnt lgkmcnt(3)
	v_pk_mul_f32 v[16:17], v[16:17], v[152:153]
	s_waitcnt lgkmcnt(2)
	v_pk_mul_f32 v[12:13], v[12:13], v[156:157]
	s_waitcnt lgkmcnt(1)
	v_pk_mul_f32 v[8:9], v[8:9], v[160:161]
	s_waitcnt lgkmcnt(0)
	v_pk_mul_f32 v[4:5], v[4:5], v[174:175]
	v_pk_mul_f32 v[14:15], v[14:15], v[150:151]
	v_pk_mul_f32 v[10:11], v[10:11], v[154:155]
	v_pk_mul_f32 v[6:7], v[6:7], v[158:159]
	v_pk_mul_f32 v[2:3], v[2:3], v[172:173]
	v_pk_mul_f32 v[64:65], v[64:65], v[152:153]
	v_pk_mul_f32 v[60:61], v[60:61], v[156:157]
	v_pk_mul_f32 v[56:57], v[56:57], v[160:161]
	v_pk_mul_f32 v[52:53], v[52:53], v[174:175]
	v_pk_mul_f32 v[62:63], v[62:63], v[150:151]
	v_pk_mul_f32 v[58:59], v[58:59], v[154:155]
	v_pk_mul_f32 v[54:55], v[54:55], v[158:159]
	v_pk_mul_f32 v[50:51], v[50:51], v[172:173]
	v_pk_mul_f32 v[48:49], v[48:49], v[152:153]
	v_pk_mul_f32 v[44:45], v[44:45], v[156:157]
	v_pk_mul_f32 v[40:41], v[40:41], v[160:161]
	v_pk_mul_f32 v[36:37], v[36:37], v[174:175]
	v_pk_mul_f32 v[46:47], v[46:47], v[150:151]
	v_pk_mul_f32 v[42:43], v[42:43], v[154:155]
	v_pk_mul_f32 v[38:39], v[38:39], v[158:159]
	v_pk_mul_f32 v[34:35], v[34:35], v[172:173]
	v_pk_mul_f32 v[32:33], v[32:33], v[152:153]
	v_pk_mul_f32 v[28:29], v[28:29], v[156:157]
	v_pk_mul_f32 v[24:25], v[24:25], v[160:161]
	v_pk_mul_f32 v[20:21], v[20:21], v[174:175]
	v_pk_mul_f32 v[30:31], v[30:31], v[150:151]
	v_pk_mul_f32 v[26:27], v[26:27], v[154:155]
	v_pk_mul_f32 v[22:23], v[22:23], v[158:159]
	v_pk_mul_f32 v[18:19], v[18:19], v[172:173]
; __device__ __forceinline__ void partialSM(f32x16& p0, f32x16& p1, float& m_reg, float& mn, float& alpha) {
;     ...
;     const float mnL = -mn * C2;
; #pragma unroll
;     for (int r = 0; r < 16; ++r) p0[r] = fmaf(p0[r], C2, mnL);
; #pragma unroll
;     for (int r = 0; r < 16; ++r) p1[r] = fmaf(p1[r], C2, mnL);
; #pragma unroll
;     for (int r = 0; r < 16; ++r) p0[r] = __builtin_amdgcn_exp2f(p0[r]);
; }
; __device__ __forceinline__ void finishSM(f32x16& p0, f32x16& p1, float alpha, float& l_reg, bf16x8& pa0, bf16x8& pa1, bf16x8& pa2, bf16x8& pa3) {
; #pragma unroll
;     for (int r = 0; r < 16; ++r) p1[r] = __builtin_amdgcn_exp2f(p1[r]);
;     float ps = 0;
; #pragma unroll
;     for (int r = 0; r < 16; ++r) ps += p0[r];
; #pragma unroll
;     for (int r = 0; r < 16; ++r) ps += p1[r];
;     { auto rr = __builtin_amdgcn_permlane32_swap(__float_as_uint(ps), __float_as_uint(ps), false, false);
;       ps = __uint_as_float(rr[0]) + __uint_as_float(rr[1]); }
;     l_reg = l_reg * alpha + ps;
;     ...
;     PK4(p0, 0, pa0); PK4(p0, 8, pa1); PK4(p1, 0, pa2); PK4(p1, 8, pa3);
.LBB0_1303:
	v_fmamk_f32 v94, v146, 0x3e0293ee, v190
	v_fmamk_f32 v82, v82, 0x3e0293ee, v190
	v_fmamk_f32 v83, v83, 0x3e0293ee, v190
	v_fmamk_f32 v95, v147, 0x3e0293ee, v190
	v_fmamk_f32 v96, v148, 0x3e0293ee, v190
	v_fmamk_f32 v97, v149, 0x3e0293ee, v190
	v_fmamk_f32 v87, v87, 0x3e0293ee, v190
	v_fmamk_f32 v88, v88, 0x3e0293ee, v190
	v_fmamk_f32 v89, v89, 0x3e0293ee, v190
	v_fmamk_f32 v90, v90, 0x3e0293ee, v190
	v_fmamk_f32 v91, v91, 0x3e0293ee, v190
	v_fmamk_f32 v92, v92, 0x3e0293ee, v190
	v_fmamk_f32 v93, v93, 0x3e0293ee, v190
	v_fmamk_f32 v79, v79, 0x3e0293ee, v190
	v_fmamk_f32 v80, v80, 0x3e0293ee, v190
	v_fmamk_f32 v81, v81, 0x3e0293ee, v190
	v_exp_f32_e32 v146, v94
	v_exp_f32_e32 v147, v82
	v_exp_f32_e32 v148, v83
	v_exp_f32_e32 v159, v95
	v_exp_f32_e32 v160, v96
	v_exp_f32_e32 v161, v97
	v_exp_f32_e32 v149, v87
	v_exp_f32_e32 v158, v88
	v_exp_f32_e32 v150, v89
	v_exp_f32_e32 v151, v90
	v_exp_f32_e32 v155, v91
	v_exp_f32_e32 v157, v92
	v_exp_f32_e32 v152, v93
	v_exp_f32_e32 v153, v79
	v_exp_f32_e32 v154, v80
	v_exp_f32_e32 v156, v81
	v_fmamk_f32 v210, v71, 0x3e0293ee, v190
	v_fmamk_f32 v209, v78, 0x3e0293ee, v190
	v_fmamk_f32 v217, v66, 0x3e0293ee, v190
	v_fmamk_f32 v218, v67, 0x3e0293ee, v190
	v_fmamk_f32 v219, v68, 0x3e0293ee, v190
	v_fmamk_f32 v220, v69, 0x3e0293ee, v190
	v_fmamk_f32 v221, v70, 0x3e0293ee, v190
	v_fmamk_f32 v211, v72, 0x3e0293ee, v190
	v_fmamk_f32 v212, v84, 0x3e0293ee, v190
	v_fmamk_f32 v213, v85, 0x3e0293ee, v190
	v_fmamk_f32 v214, v86, 0x3e0293ee, v190
	v_fmamk_f32 v215, v76, 0x3e0293ee, v190
	v_fmamk_f32 v216, v77, 0x3e0293ee, v190
	v_fmamk_f32 v222, v73, 0x3e0293ee, v190
	v_fmamk_f32 v223, v74, 0x3e0293ee, v190
	v_fmamk_f32 v207, v75, 0x3e0293ee, v190
	v_exp_f32_e32 v211, v211
	v_exp_f32_e32 v212, v212
	v_exp_f32_e32 v213, v213
	v_exp_f32_e32 v214, v214
	v_exp_f32_e32 v215, v215
	v_exp_f32_e32 v216, v216
	v_exp_f32_e32 v207, v207
	v_exp_f32_e32 v250, v219
	v_exp_f32_e32 v219, v209
	v_add_f32_e32 v209, v147, v146
	v_add_f32_e32 v209, v148, v209
	v_add_f32_e32 v209, v159, v209
	v_add_f32_e32 v209, v160, v209
	v_add_f32_e32 v209, v161, v209
	v_add_f32_e32 v209, v149, v209
	v_add_f32_e32 v209, v158, v209
	v_add_f32_e32 v209, v150, v209
	v_add_f32_e32 v209, v151, v209
	v_add_f32_e32 v209, v155, v209
	v_add_f32_e32 v209, v157, v209
	v_exp_f32_e32 v248, v217
	v_add_f32_e32 v209, v152, v209
	v_exp_f32_e32 v249, v218
	v_add_f32_e32 v209, v153, v209
	v_add_f32_e32 v209, v154, v209
	v_exp_f32_e32 v251, v220
	v_add_f32_e32 v209, v156, v209
	v_exp_f32_e32 v217, v221
	v_add_f32_e32 v209, v248, v209
	v_exp_f32_e32 v218, v210
	v_add_f32_e32 v209, v249, v209
	v_add_f32_e32 v209, v250, v209
	v_add_f32_e32 v209, v251, v209
	v_add_f32_e32 v209, v217, v209
	v_add_f32_e32 v209, v218, v209
	v_add_f32_e32 v209, v211, v209
	v_add_f32_e32 v209, v212, v209
	v_add_f32_e32 v209, v213, v209
	v_exp_f32_e32 v220, v222
	v_add_f32_e32 v209, v214, v209
	v_exp_f32_e32 v221, v223
	v_add_f32_e32 v209, v215, v209
	v_add_f32_e32 v209, v216, v209
	v_add_f32_e32 v209, v219, v209
	v_add_f32_e32 v209, v220, v209
	v_add_f32_e32 v209, v221, v209
	v_add_f32_e32 v209, v207, v209
	v_cvt_pk_bf16_f32 v146, v146, v147
	v_cvt_pk_bf16_f32 v147, v148, v159
	v_cvt_pk_bf16_f32 v148, v160, v161
	v_cvt_pk_bf16_f32 v149, v149, v158
	v_cvt_pk_bf16_f32 v150, v150, v151
	v_cvt_pk_bf16_f32 v151, v155, v157
	v_cvt_pk_bf16_f32 v152, v152, v153
	v_cvt_pk_bf16_f32 v153, v154, v156
	v_cvt_pk_bf16_f32 v154, v248, v249
	v_cvt_pk_bf16_f32 v155, v250, v251
	v_cvt_pk_bf16_f32 v156, v217, v218
	v_cvt_pk_bf16_f32 v157, v211, v212
	v_cvt_pk_bf16_f32 v158, v213, v214
	v_cvt_pk_bf16_f32 v159, v215, v216
	v_cvt_pk_bf16_f32 v160, v219, v220
	v_cvt_pk_bf16_f32 v161, v221, v207
	s_waitcnt lgkmcnt(0)
	s_barrier
	s_waitcnt vmcnt(2)
	ds_write_b128 v197, v[130:133]
	ds_write_b128 v198, v[134:137]
	global_load_dwordx2 v[228:229], v179, s[68:69]
	s_add_i32 s98, s82, 2
	s_cmp_gt_u32 s98, s81
	s_cbranch_scc1 .Lp5_a2
	s_add_u32 s98, s16, 0x60000
	s_addc_u32 s99, s17, 0
	global_load_dwordx4 v[130:133], v188, s[98:99]
	s_add_u32 s98, s16, 0x70000
	s_addc_u32 s99, s17, 0
	global_load_dwordx4 v[134:137], v188, s[98:99]

; __device__ __forceinline__ void sel_mask_tile(f32x16& p0, f32x16& p1, unsigned wlo, unsigned whi, int hi) {
;     const unsigned NEGB = 0xff800000u;
;     const unsigned lo = wlo >> (4 * hi), h2 = whi >> (4 * hi);
; #pragma unroll
;     for (int r = 0; r < 16; ++r) {
;         const int c = (r & 3) + 8 * (r >> 2);
;         const unsigned m0 = (unsigned)__builtin_amdgcn_sbfe((int)lo, c, 1), m1 = (unsigned)__builtin_amdgcn_sbfe((int)h2, c, 1);
;         p0[r] = __uint_as_float((__float_as_uint(p0[r]) & m0) | (NEGB & ~m0));
;         p1[r] = __uint_as_float((__float_as_uint(p1[r]) & m1) | (NEGB & ~m1));
;     }
; }
; __device__ __forceinline__ void partialSM(f32x16& p0, f32x16& p1, float& m_reg, float& mn, float& alpha) {
;     float pmax = p0[0];
; #pragma unroll
;     for (int r = 1; r < 16; ++r) pmax = fmaxf(pmax, p0[r]);
; #pragma unroll
;     for (int r = 0; r < 16; ++r) pmax = fmaxf(pmax, p1[r]);
;     { auto rr = __builtin_amdgcn_permlane32_swap(__float_as_uint(pmax), __float_as_uint(pmax), false, false);
;       pmax = fmaxf(__uint_as_float(rr[0]), __uint_as_float(rr[1])); }
;     constexpr float C2 = 1.4426950408889634f * SCALE;
;     if (__builtin_expect(__all((pmax - m_reg) * SCALE <= THR), 1)) { mn = m_reg; alpha = 1.f; }
;     else { mn = fmaxf(m_reg, pmax); alpha = __builtin_amdgcn_exp2f((m_reg - mn) * C2); m_reg = mn; }
; template <int VB>
; __device__ __forceinline__ void pv_tile(f32x16* o, int vb0, bf16x8 pa0, bf16x8 pa1, bf16x8 pa2, bf16x8 pa3) {
;     ...
;     PV_D0(0); PV_D0(1); PV_D0(2); PV_D0(3);
;     ...
; }
.LBB0_1305:
	ds_read_b64_tr_b16 v[172:173], v1 offset:0x5000
	ds_read_b64_tr_b16 v[174:175], v1 offset:0x5800
	ds_read_b64_tr_b16 v[224:225], v1 offset:0x5200
	ds_read_b64_tr_b16 v[226:227], v1 offset:0x5a00
	ds_read_b64_tr_b16 v[232:233], v1 offset:0x5400
	ds_read_b64_tr_b16 v[234:235], v1 offset:0x5c00
	s_waitcnt lgkmcnt(12)
	v_mfma_f32_32x32x16_bf16 v[2:17], v[146:149], v[212:215], v[2:17]
	ds_read_b64_tr_b16 v[236:237], v1 offset:0x5600
	ds_read_b64_tr_b16 v[238:239], v1 offset:0x5e00
	s_waitcnt lgkmcnt(12)
	v_mfma_f32_32x32x16_bf16 v[50:65], v[146:149], v[216:219], v[50:65]
	ds_read_b64_tr_b16 v[240:241], v1 offset:0x6000
	ds_read_b64_tr_b16 v[242:243], v1 offset:0x6800
	s_waitcnt lgkmcnt(12)
	v_mfma_f32_32x32x16_bf16 v[34:49], v[146:149], v[220:223], v[34:49]
	ds_read_b64_tr_b16 v[244:245], v1 offset:0x6200
	ds_read_b64_tr_b16 v[246:247], v1 offset:0x6a00
	s_waitcnt lgkmcnt(12)
	v_mfma_f32_32x32x16_bf16 v[18:33], v[146:149], v[248:251], v[18:33]
	ds_read_b64_tr_b16 v[248:249], v1 offset:0x6400
	ds_read_b64_tr_b16 v[250:251], v1 offset:0x6c00
	s_waitcnt lgkmcnt(12)
	v_mfma_f32_32x32x16_bf16 v[2:17], v[150:153], v[172:175], v[2:17]
	ds_read_b64_tr_b16 v[172:173], v1 offset:0x6600
	ds_read_b64_tr_b16 v[174:175], v1 offset:0x6e00
	s_waitcnt lgkmcnt(12)
	v_mfma_f32_32x32x16_bf16 v[50:65], v[150:153], v[224:227], v[50:65]
	ds_read_b64_tr_b16 v[224:225], v1 offset:0x7000
	ds_read_b64_tr_b16 v[226:227], v1 offset:0x7800
	s_waitcnt lgkmcnt(12)
	v_mfma_f32_32x32x16_bf16 v[34:49], v[150:153], v[232:235], v[34:49]
	ds_read_b64_tr_b16 v[232:233], v1 offset:0x7200
	ds_read_b64_tr_b16 v[234:235], v1 offset:0x7a00
	s_waitcnt lgkmcnt(12)
	v_mfma_f32_32x32x16_bf16 v[18:33], v[150:153], v[236:239], v[18:33]
	ds_read_b64_tr_b16 v[236:237], v1 offset:0x7400
	ds_read_b64_tr_b16 v[238:239], v1 offset:0x7c00
	s_waitcnt lgkmcnt(12)
	v_mfma_f32_32x32x16_bf16 v[2:17], v[154:157], v[240:243], v[2:17]
	ds_read_b64_tr_b16 v[240:241], v1 offset:0x7600
	ds_read_b64_tr_b16 v[242:243], v1 offset:0x7e00
	s_waitcnt lgkmcnt(12)
	v_mfma_f32_32x32x16_bf16 v[50:65], v[154:157], v[244:247], v[50:65]
	s_waitcnt lgkmcnt(10)
	v_mfma_f32_32x32x16_bf16 v[34:49], v[154:157], v[248:251], v[34:49]
	s_waitcnt lgkmcnt(8)
	v_mfma_f32_32x32x16_bf16 v[18:33], v[154:157], v[172:175], v[18:33]
	s_waitcnt lgkmcnt(6)
	v_mfma_f32_32x32x16_bf16 v[2:17], v[158:161], v[224:227], v[2:17]
	s_waitcnt lgkmcnt(4)
	v_mfma_f32_32x32x16_bf16 v[50:65], v[158:161], v[232:235], v[50:65]
	s_waitcnt lgkmcnt(2)
	v_mfma_f32_32x32x16_bf16 v[34:49], v[158:161], v[236:239], v[34:49]
	s_waitcnt lgkmcnt(0)
	v_mfma_f32_32x32x16_bf16 v[18:33], v[158:161], v[240:243], v[18:33]
	s_cmp_eq_u64 s[36:37], 0
	s_cbranch_scc1 .Lp5_kw2_skip
	s_waitcnt vmcnt(3)
	ds_write_b128 v204, v[138:141] offset:49152
	ds_write_b128 v204, v[142:145] offset:57344
.Lp5_kw2_skip:
	s_waitcnt lgkmcnt(0)
	s_barrier
	s_nop 0
	s_waitcnt vmcnt(2)
	v_lshrrev_b32_e32 v193, v163, v228
	v_bfe_i32 v192, v193, 0, 1
	v_bitop3_b32 v192, v82, s74, v192 bitop3:0xe4
	v_bfe_i32 v82, v193, 1, 1
	v_bitop3_b32 v146, v83, s74, v82 bitop3:0xe4
	v_bfe_i32 v82, v193, 2, 1
	v_bitop3_b32 v147, v84, s74, v82 bitop3:0xe4
	v_bfe_i32 v82, v193, 3, 1
	v_bitop3_b32 v148, v85, s74, v82 bitop3:0xe4
	v_bfe_i32 v82, v193, 8, 1
	v_bitop3_b32 v149, v86, s74, v82 bitop3:0xe4
	v_bfe_i32 v82, v193, 9, 1
	v_bitop3_b32 v150, v87, s74, v82 bitop3:0xe4
	v_bfe_i32 v82, v193, 10, 1
	v_bitop3_b32 v88, v88, s74, v82 bitop3:0xe4
	v_bfe_i32 v82, v193, 11, 1
	v_bitop3_b32 v89, v89, s74, v82 bitop3:0xe4
	v_bfe_i32 v82, v193, 16, 1
	v_bitop3_b32 v90, v90, s74, v82 bitop3:0xe4
	v_bfe_i32 v82, v193, 17, 1
	v_bitop3_b32 v91, v91, s74, v82 bitop3:0xe4
	v_bfe_i32 v82, v193, 18, 1
	v_bitop3_b32 v92, v92, s74, v82 bitop3:0xe4
	v_bfe_i32 v82, v193, 19, 1
	v_bitop3_b32 v93, v93, s74, v82 bitop3:0xe4
	v_bfe_i32 v82, v193, 24, 1
	v_bitop3_b32 v94, v94, s74, v82 bitop3:0xe4
	v_bfe_i32 v82, v193, 25, 1
	v_bitop3_b32 v95, v95, s74, v82 bitop3:0xe4
	v_bfe_i32 v82, v193, 26, 1
	v_bitop3_b32 v96, v96, s74, v82 bitop3:0xe4
	v_bfe_i32 v82, v193, 27, 1
	v_bitop3_b32 v97, v97, s74, v82 bitop3:0xe4
	v_max_f32_e32 v82, v192, v146
	v_max3_f32 v82, v82, v147, v148
	v_max3_f32 v82, v82, v149, v150
	v_max3_f32 v82, v82, v88, v89
	v_max3_f32 v82, v82, v90, v91
	v_lshrrev_b32_e32 v194, v163, v229
	v_max3_f32 v82, v82, v92, v93
	v_bfe_i32 v195, v194, 0, 1
	v_bfe_i32 v172, v194, 1, 1
	v_max3_f32 v82, v82, v94, v95
	v_bitop3_b32 v66, v66, s74, v195 bitop3:0xe4
	v_bfe_i32 v83, v194, 2, 1
	v_bfe_i32 v84, v194, 3, 1
	v_max3_f32 v230, v82, v96, v97
	v_bitop3_b32 v67, v67, s74, v172 bitop3:0xe4
	v_bfe_i32 v85, v194, 8, 1
	v_bfe_i32 v86, v194, 9, 1
	v_bitop3_b32 v82, v68, s74, v83 bitop3:0xe4
	v_max3_f32 v68, v230, v66, v67
	v_bitop3_b32 v83, v69, s74, v84 bitop3:0xe4
	v_bfe_i32 v87, v194, 10, 1
	v_bfe_i32 v151, v194, 11, 1
	v_bitop3_b32 v84, v70, s74, v85 bitop3:0xe4
	v_max3_f32 v68, v68, v82, v83
	v_bitop3_b32 v85, v71, s74, v86 bitop3:0xe4
	v_bfe_i32 v152, v194, 16, 1
	v_bfe_i32 v153, v194, 17, 1
	v_bitop3_b32 v86, v72, s74, v87 bitop3:0xe4
	v_max3_f32 v68, v68, v84, v85
	v_bitop3_b32 v87, v73, s74, v151 bitop3:0xe4
	v_bfe_i32 v154, v194, 18, 1
	v_bfe_i32 v155, v194, 19, 1
	v_bitop3_b32 v74, v74, s74, v152 bitop3:0xe4
	v_max3_f32 v69, v68, v86, v87
	v_bitop3_b32 v75, v75, s74, v153 bitop3:0xe4
	v_bfe_i32 v156, v194, 24, 1
	v_bfe_i32 v157, v194, 25, 1
	v_bitop3_b32 v68, v76, s74, v154 bitop3:0xe4
	v_max3_f32 v71, v69, v74, v75
	v_bitop3_b32 v69, v77, s74, v155 bitop3:0xe4
	v_bfe_i32 v230, v194, 26, 1
	v_bfe_i32 v231, v194, 27, 1
	v_bitop3_b32 v70, v78, s74, v156 bitop3:0xe4
	v_max3_f32 v73, v71, v68, v69
	v_bitop3_b32 v71, v79, s74, v157 bitop3:0xe4
	v_bitop3_b32 v72, v80, s74, v230 bitop3:0xe4
	v_max3_f32 v76, v73, v70, v71
	v_bitop3_b32 v73, v81, s74, v231 bitop3:0xe4
	v_max3_f32 v76, v76, v72, v73
	v_mov_b32_e32 v77, v76
	s_nop 1
	v_permlane32_swap_b32_e32 v76, v77
	v_max_f32_e32 v76, v76, v77
	v_sub_f32_e32 v77, v76, v206
	v_mul_f32_e32 v77, 0x3db504f3, v77
	v_cmp_ge_f32_e32 vcc, s75, v77
	s_cmp_eq_u64 vcc, exec
	s_cselect_b64 s[6:7], -1, 0

; #define SBAR() __builtin_amdgcn_sched_barrier(0)
; #define SLOAD_H(Kp, Vp, k0) do { S.st_v0 = load8(ROW(Vp, k0, sr)); S.st_v1 = load8(ROW(Vp, k0, 32 + sr));              \
;                          S.st_k0 = load8(ROW(Kp, k0, sr)); S.st_k1 = load8(ROW(Kp, k0, 32 + sr)); } while (0)
; #define RESC(a) do { if (__any((a) < 1.f)) { if (hi == 0) al_l[r32] = (a); asm volatile("s_waitcnt lgkmcnt(0)" ::: "memory");              \
;                      for (int d_ = 0; d_ < 4; ++d_) for (int r = 0; r < 16; ++r) o[d_][r] *= al_l[crow(r, hi)]; } } while (0)
; #define MASKT(P0_, P1_) sel_mask_tile(P0_, P1_, mw.x, mw.y, hi)
; #define SEAM_K0() do { VMWN(NQL); SWRITE_HK(0); SBAR(); } while (0)
; __device__ __forceinline__ void attn_block(const BlockRef& cur, const BlockRef& nxt, char* lds, Seam& S) {
;     ...
;     mw = LDMASK(NT - 1);
;     SBAR(); qkt<1>(pB0, pB1, K_lds, r32, hi, S.qr); SBAR();
;     SLOAD_H(nxt.K, nxt.V, 0); SBAR();
; #pragma unroll
;     for (int d0 = 0; d0 < 8; ++d0) S.qr[d0] = load8(nxt.Q + (size_t)(wid * QBLK + r32) * LD + d0 * 16 + hi * 8);
;     SBAR();
;     finishSM(pA0, pA1, alA, l_reg, pa0, pa1, pa2, pa3); SBAR();
;     pv_tile<0>(o, vb0, pa0, pa1, pa2, pa3);
;     MASKT(pB0, pB1); partialSM(pB0, pB1, m_reg, mnB, alB); __syncthreads(); RESC(alB);
;     finishSM(pB0, pB1, alB, l_reg, pa0, pa1, pa2, pa3); SBAR(); pv_tile<1>(o, vb0, pa0, pa1, pa2, pa3);
;     SBAR(); SEAM_K0();
;     if (hi == 0) li_l[r32] = l_reg; asm volatile("s_waitcnt lgkmcnt(0)" ::: "memory");
.Lp5_exit:
	s_waitcnt vmcnt(0)
	s_cmp_lg_u32 s77, 0
	s_cbranch_scc1 .Lp5_exit_b
	s_waitcnt lgkmcnt(0)
	s_barrier
